# v63 + diff loop: exps/row-sum of key-blocks 2-4 interleaved into the PV MFMA gaps (V fragment buffers renamed to v188-203, row-sum in v185)
# speedup vs baseline: 1.0119x; 1.0119x over previous
; #define MFMA32(a, b, c) __builtin_amdgcn_mfma_f32_32x32x16_bf16((a), (b), (c), 0, 0, 0)
; template <int DQK, int KROW, bool BIAS, bool MAPS2>
; DI void attn_core(const int t, const u16* __restrict__ Q, int ldq, const u16* __restrict__ Kp, int ldk, const u16* __restrict__ Vt, int q0,
;                   char* lds, const float* lut, float b31, f32x16 (&o)[4], float& l_out) {
;     ...
;       float ps = 0.f;
; #pragma unroll
;       for (int k2 = 0; k2 < 2; ++k2)
; #pragma unroll
;         for (int i = 0; i < 16; ++i) { const float pv = __builtin_amdgcn_exp2f(s[k2][i]); s[k2][i] = pv; ps += pv; }
;       l_run += ps;
;       bf16x8 vfb[2][4];
;       const char* vbase = lds + AT_VOFF + (kt & 1) * AT_VBUF + r * VS + hf * 16;
; #pragma unroll
;       for (int dt = 0; dt < 4; ++dt) vfb[0][dt] = *(const bf16x8*)(vbase + 32 * dt * VS);
; #pragma unroll
;       for (int bb = 0; bb < 4; ++bb) {
;         const int k2 = bb >> 1, s2 = bb & 1;
;         if (bb + 1 < 4) {
; #pragma unroll
;           for (int dt = 0; dt < 4; ++dt) vfb[(bb + 1) & 1][dt] = *(const bf16x8*)(vbase + 32 * dt * VS + (bb + 1) * 32);
;         }
;         u32x4 pp;
;         pp[0] = pk_bf16(s[k2][8 * s2 + 0], s[k2][8 * s2 + 1]);
;         pp[1] = pk_bf16(s[k2][8 * s2 + 2], s[k2][8 * s2 + 3]);
;         pp[2] = pk_bf16(s[k2][8 * s2 + 4], s[k2][8 * s2 + 5]);
;         pp[3] = pk_bf16(s[k2][8 * s2 + 6], s[k2][8 * s2 + 7]);
;         const bf16x8 pf = __builtin_bit_cast(bf16x8, pp);
;         __builtin_amdgcn_sched_barrier(0);
;         __builtin_amdgcn_s_setprio(1);
; #pragma unroll
;         for (int dt = 0; dt < 4; ++dt) o[dt] = MFMA32(vfb[bb & 1][dt], pf, o[dt]);
;         __builtin_amdgcn_s_setprio(0);
;         __builtin_amdgcn_sched_barrier(0);
;       }
.LBB0_242:
	v_exp_f32_e32 v0, v96
	v_exp_f32_e32 v14, v97
	v_exp_f32_e32 v15, v98
	v_exp_f32_e32 v162, v99
	v_add_f32_e32 v185, 0, v0
	v_exp_f32_e32 v163, v100
	v_add_f32_e32 v185, v14, v185
	v_exp_f32_e32 v164, v101
	v_add_f32_e32 v185, v15, v185
	v_exp_f32_e32 v165, v102
	v_add_f32_e32 v185, v162, v185
	v_exp_f32_e32 v103, v103
	v_add_f32_e32 v185, v163, v185
	s_mulk_i32 s91, 0x4800
	v_add_u32_e32 v183, s91, v158
	ds_read_b128 v[2:5], v183 offset:51200
	ds_read_b128 v[6:9], v183 offset:51232
	ds_read_b128 v[10:13], v183 offset:55808
	ds_read_b128 v[188:191], v183 offset:55840
	ds_read_b128 v[192:195], v183 offset:60416
	ds_read_b128 v[196:199], v183 offset:60448
	ds_read_b128 v[200:203], v183 offset:65024
	ds_read_b128 v[96:99], v183 offset:65056
	v_cvt_pk_bf16_f32 v100, v0, v14
	v_cvt_pk_bf16_f32 v101, v15, v162
	v_cvt_pk_bf16_f32 v102, v163, v164
	v_cvt_pk_bf16_f32 v103, v165, v103
	s_setprio 1
	s_waitcnt lgkmcnt(7)
	v_mfma_f32_32x32x16_bf16 v[64:79], v[2:5], v[100:103], v[64:79]
	v_exp_f32_e32 v104, v104
	v_exp_f32_e32 v105, v105
	v_add_f32_e32 v185, v164, v185
	v_add_f32_e32 v185, v165, v185
	s_waitcnt lgkmcnt(5)
	v_mfma_f32_32x32x16_bf16 v[48:63], v[10:13], v[100:103], v[48:63]
	v_exp_f32_e32 v106, v106
	v_exp_f32_e32 v107, v107
	v_add_f32_e32 v185, v103, v185
	v_add_f32_e32 v185, v104, v185
	s_waitcnt lgkmcnt(3)
	v_mfma_f32_32x32x16_bf16 v[32:47], v[192:195], v[100:103], v[32:47]
	v_exp_f32_e32 v108, v108
	v_exp_f32_e32 v109, v109
	v_add_f32_e32 v185, v105, v185
	v_add_f32_e32 v185, v106, v185
	s_waitcnt lgkmcnt(1)
	v_mfma_f32_32x32x16_bf16 v[16:31], v[200:203], v[100:103], v[16:31]
	v_exp_f32_e32 v110, v110
	v_exp_f32_e32 v111, v111
	v_add_f32_e32 v185, v107, v185
	v_add_f32_e32 v185, v108, v185
	s_setprio 0
	ds_read_b128 v[2:5], v183 offset:51264
	ds_read_b128 v[10:13], v183 offset:55872
	ds_read_b128 v[192:195], v183 offset:60480
	ds_read_b128 v[200:203], v183 offset:65088
	v_cvt_pk_bf16_f32 v100, v104, v105
	v_cvt_pk_bf16_f32 v101, v106, v107
	v_cvt_pk_bf16_f32 v102, v108, v109
	v_cvt_pk_bf16_f32 v103, v110, v111
	s_setprio 1
	s_nop 0
	v_mfma_f32_32x32x16_bf16 v[64:79], v[6:9], v[100:103], v[64:79]
	v_exp_f32_e32 v166, v80
	v_exp_f32_e32 v167, v81
	v_add_f32_e32 v185, v109, v185
	v_add_f32_e32 v185, v110, v185
	v_mfma_f32_32x32x16_bf16 v[48:63], v[188:191], v[100:103], v[48:63]
	v_exp_f32_e32 v168, v82
	v_exp_f32_e32 v169, v83
	v_add_f32_e32 v185, v111, v185
	v_add_f32_e32 v185, v166, v185
	v_mfma_f32_32x32x16_bf16 v[32:47], v[196:199], v[100:103], v[32:47]
	v_exp_f32_e32 v170, v84
	v_exp_f32_e32 v171, v85
	v_add_f32_e32 v185, v167, v185
	v_add_f32_e32 v185, v168, v185
	s_waitcnt lgkmcnt(4)
	v_mfma_f32_32x32x16_bf16 v[16:31], v[96:99], v[100:103], v[16:31]
	v_exp_f32_e32 v172, v86
	v_exp_f32_e32 v173, v87
	v_add_f32_e32 v185, v169, v185
	v_add_f32_e32 v185, v170, v185
	s_setprio 0
	ds_read_b128 v[6:9], v183 offset:51296
	ds_read_b128 v[188:191], v183 offset:55904
	ds_read_b128 v[196:199], v183 offset:60512
	ds_read_b128 v[96:99], v183 offset:65120
	v_cvt_pk_bf16_f32 v100, v166, v167
	v_cvt_pk_bf16_f32 v101, v168, v169
	v_cvt_pk_bf16_f32 v102, v170, v171
	v_cvt_pk_bf16_f32 v103, v172, v173
	s_setprio 1
	s_waitcnt lgkmcnt(7)
	v_mfma_f32_32x32x16_bf16 v[64:79], v[2:5], v[100:103], v[64:79]
	v_exp_f32_e32 v174, v88
	v_exp_f32_e32 v175, v89
	v_add_f32_e32 v185, v171, v185
	v_add_f32_e32 v185, v172, v185
	s_waitcnt lgkmcnt(6)
	v_mfma_f32_32x32x16_bf16 v[48:63], v[10:13], v[100:103], v[48:63]
	v_exp_f32_e32 v176, v90
	v_exp_f32_e32 v177, v91
	v_add_f32_e32 v185, v173, v185
	v_add_f32_e32 v185, v174, v185
	s_waitcnt lgkmcnt(5)
	v_mfma_f32_32x32x16_bf16 v[32:47], v[192:195], v[100:103], v[32:47]
	v_exp_f32_e32 v178, v92
	v_exp_f32_e32 v179, v93
	v_add_f32_e32 v185, v175, v185
	v_add_f32_e32 v185, v176, v185
	s_waitcnt lgkmcnt(4)
	v_mfma_f32_32x32x16_bf16 v[16:31], v[200:203], v[100:103], v[16:31]
	v_exp_f32_e32 v180, v94
	v_exp_f32_e32 v181, v95
	v_add_f32_e32 v185, v177, v185
	v_add_f32_e32 v185, v178, v185
	s_setprio 0
	v_cvt_pk_bf16_f32 v2, v174, v175
	v_cvt_pk_bf16_f32 v3, v176, v177
	v_cvt_pk_bf16_f32 v4, v178, v179
	v_cvt_pk_bf16_f32 v5, v180, v181
	s_setprio 1
	s_waitcnt lgkmcnt(3)
	v_mfma_f32_32x32x16_bf16 v[64:79], v[6:9], v[2:5], v[64:79]
	v_add_f32_e32 v185, v179, v185
	v_add_f32_e32 v185, v180, v185
	s_waitcnt lgkmcnt(2)
	v_mfma_f32_32x32x16_bf16 v[48:63], v[188:191], v[2:5], v[48:63]
	v_add_f32_e32 v182, v181, v185
	s_waitcnt lgkmcnt(1)
	v_mfma_f32_32x32x16_bf16 v[32:47], v[196:199], v[2:5], v[32:47]
	s_waitcnt lgkmcnt(0)
	v_mfma_f32_32x32x16_bf16 v[16:31], v[96:99], v[2:5], v[16:31]
	s_setprio 0
	v_add_f32_e32 v151, v151, v182
